# mixer work queue: next-item ticket atomic result left in a dead VGPR and read at the loop tail (its round trip no longer sits in front of every item)
# baseline (speedup 1.0000x reference)
; __global__ void __launch_bounds__(NTHR, 2) fwd_kernel(Args args) {
;     ...
;             unsigned* qhead = ctl + CW_QUEUE + 64 * (l + 4 * rep);
;             int it = F.bid;
;             if (F.G == 256) { const int x = F.bid & 7, j = F.bid >> 3; it = ((x >> 2) << 7) | (((j >> 1) & 1) << 6) | ((8 * (x & 3) + (j >> 2)) << 1) | (j & 1); }
;             unsigned nxt = 0u;
;             if (F.tid == 0) nxt = __hip_atomic_fetch_add(qhead, 1u, __ATOMIC_RELAXED, __HIP_MEMORY_SCOPE_AGENT) + (unsigned)F.G;
;             while (it < W_END) {
;                 { int t_ = threadIdx.x; asm volatile("" : "+v"(t_)); F.tid = t_; F.lane = t_ & 63; F.wave = __builtin_amdgcn_readfirstlane(t_ >> 6); }
;                 if (it < W_ATT) { _Pragma("unroll 1") for (int rr = 0; rr < (PROBE_DUP == 61 ? 2 : 1); ++rr) attn_item_mfma(F, args, l, it); }
;                 else if (it < W_CFFT) fft_item<8>(F, args, it - W_ATT);
;                 else if (it < W_FFT) { _Pragma("unroll 1") for (int rr = 0; rr < (PROBE_DUP == 62 ? 2 : 1); ++rr) fft_item<12>(F, args, it - W_CFFT); }
;                 else if (it < W_CONV) { _Pragma("unroll 1") for (int rr = 0; rr < (PROBE_DUP == 63 ? 2 : 1); ++rr) conv_tile_v1(F, args, l, it - W_FFT); }
;                 else { ssm_sgemm_item(F, args, l, it - W_CONV); if (PROBE_DUP == 64) ssm_sgemm_item(F, args, l, it - W_CONV); }
;                 if (threadIdx.x == 0) MISC[0] = nxt;
;                 __syncthreads();
;                 it = __builtin_amdgcn_readfirstlane((int)MISC[0]);
;                 if (threadIdx.x == 0 && it < W_END) nxt = __hip_atomic_fetch_add(qhead, 1u, __ATOMIC_RELAXED, __HIP_MEMORY_SCOPE_AGENT) + (unsigned)F.G;
.LBB0_1261:
	s_andn2_b64 vcc, exec, s[0:1]
	s_cbranch_vccnz .LBB0_1575
	v_readlane_b32 s0, v254, 15
	s_lshl_b32 s4, s0, 6
	v_readlane_b32 s0, v250, 58
	v_readlane_b32 s1, v250, 59
	s_mov_b32 s0, s4
	s_mov_b32 s5, s1
	v_writelane_b32 v254, s0, 45
	v_mov_b32_e32 v2, v0
	s_waitcnt vmcnt(0)
	v_mov_b32_e32 v148, 0
	v_writelane_b32 v254, s1, 46
	s_lshl_b64 s[0:1], s[4:5], 2
	v_readlane_b32 s4, v252, 63
	s_add_u32 s4, s4, s0
	v_readlane_b32 s0, v253, 0
	s_addc_u32 s5, s0, s1
	v_writelane_b32 v254, s4, 47
	v_cmp_eq_u32_e32 vcc, 0, v2
	s_nop 0
	v_writelane_b32 v254, s5, 48
	s_and_saveexec_b64 s[0:1], vcc
	s_cbranch_execz .LBB0_1266
	s_mov_b64 s[6:7], exec
	v_mbcnt_lo_u32_b32 v2, s6, 0
	v_mbcnt_hi_u32_b32 v2, s7, v2
	v_cmp_eq_u32_e32 vcc, 0, v2
	s_and_saveexec_b64 s[4:5], vcc
	s_cbranch_execz .LBB0_1265
	s_bcnt1_i32_b64 s6, s[6:7]
	v_mov_b32_e32 v3, s6
	v_readlane_b32 s6, v254, 47
	v_readlane_b32 s7, v254, 48
	s_nop 4
	global_atomic_add v220, v195, v3, s[6:7] sc0
.LBB0_1265:
	s_or_b64 exec, exec, s[4:5]
.LBB0_1266:
	s_or_b64 exec, exec, s[0:1]
	v_readlane_b32 s0, v253, 46
	v_readlane_b32 s1, v253, 47
	s_andn2_b64 vcc, exec, s[0:1]
	s_cbranch_vccnz .LBB0_1521
	v_readlane_b32 s1, v254, 15
	v_readlane_b32 s4, v250, 34
	s_lshl_b32 s0, s1, 22
	v_readlane_b32 s8, v250, 38
	v_readlane_b32 s9, v250, 39
	v_readlane_b32 s10, v250, 40
	v_readlane_b32 s11, v250, 41
	v_readlane_b32 s12, v250, 42
	v_readlane_b32 s13, v250, 43
	v_readlane_b32 s14, v250, 44
	v_readlane_b32 s15, v250, 45
	v_writelane_b32 v254, s0, 49
	s_lshl_b32 s0, s1, 9
	v_readlane_b32 s16, v250, 46
	v_readlane_b32 s17, v250, 47
	v_readlane_b32 s18, v250, 48
	v_readlane_b32 s19, v250, 49
	s_mov_b64 s[8:9], s[12:13]
	v_writelane_b32 v254, s0, 50
	s_mul_i32 s0, s1, 0xf800
	s_mov_b64 s[10:11], s[14:15]
	s_mov_b64 s[12:13], s[16:17]
	v_readlane_b32 s5, v250, 35
	s_add_u32 s4, s12, s0
	s_addc_u32 s5, s13, 0
	v_writelane_b32 v254, s4, 51
	s_lshl_b32 s0, s1, 3
	s_mov_b64 s[14:15], s[18:19]
	v_writelane_b32 v254, s5, 52
	v_writelane_b32 v254, s0, 53
	v_writelane_b32 v254, s81, 54
	v_readlane_b32 s10, v253, 45
	v_readlane_b32 s14, v254, 14
	v_readlane_b32 s6, v250, 36
	v_readlane_b32 s7, v250, 37
	s_branch .LBB0_1270
.LBB0_1268:
	s_or_b64 exec, exec, s[6:7]
.LBB0_1269:
	s_or_b64 exec, exec, s[4:5]
	s_andn2_b64 vcc, exec, s[0:1]
	s_cbranch_vccz .LBB0_1521

; __global__ void __launch_bounds__(NTHR, 2) fwd_kernel(Args args) {
;     ...
;                 if (threadIdx.x == 0) MISC[0] = nxt;
;                 __syncthreads();
;                 it = __builtin_amdgcn_readfirstlane((int)MISC[0]);
;                 if (threadIdx.x == 0 && it < W_END) nxt = __hip_atomic_fetch_add(qhead, 1u, __ATOMIC_RELAXED, __HIP_MEMORY_SCOPE_AGENT) + (unsigned)F.G;
.LBB0_1517:
	s_waitcnt vmcnt(0)
	v_add_u32_e32 v148, s33, v220
	v_mov_b32_e32 v2, s14
	ds_write_b32 v2, v148
.LBB0_1518:
	s_or_b64 exec, exec, s[0:1]
	v_mov_b32_e32 v2, s14
	s_waitcnt vmcnt(0) lgkmcnt(0)
	s_barrier
	ds_read_b32 v2, v2
	s_waitcnt lgkmcnt(0)
	v_readfirstlane_b32 s10, v2
	s_cmpk_gt_i32 s10, 0x4d7
	s_cselect_b64 s[0:1], -1, 0
	s_cmpk_lt_i32 s10, 0x4d8
	s_cselect_b64 s[4:5], -1, 0
	s_and_b64 s[6:7], s[92:93], s[4:5]
	s_and_saveexec_b64 s[4:5], s[6:7]
	s_cbranch_execz .LBB0_1269
	s_mov_b64 s[8:9], exec
	v_mbcnt_lo_u32_b32 v2, s8, 0
	v_mbcnt_hi_u32_b32 v2, s9, v2
	v_cmp_eq_u32_e32 vcc, 0, v2
	s_and_saveexec_b64 s[6:7], vcc
	s_cbranch_execz .LBB0_1268
	s_bcnt1_i32_b64 s8, s[8:9]
	v_mov_b32_e32 v3, s8
	v_readlane_b32 s8, v254, 47
	v_readlane_b32 s9, v254, 48
	s_nop 4
	global_atomic_add v220, v195, v3, s[8:9] sc0
	s_branch .LBB0_1268
